# layer 0 runs 40 w_out tiles in the dual-projection tail (as layer 1 does); layer-1 conversion split 1440 / 1440 between the projection tail (136 workgroups) and the w_out tail (all workgroups)
# speedup vs baseline: 1.0030x; 1.0030x over previous
;     __device__ bool next(int i, Unit& u) const {
;         const long L = (long)i * G + c; if (L >= nwg) return false;
;         int wgid = (int)L; { const int q = nwg / NXCD, r = nwg % NXCD, xcd = wgid % NXCD, off = wgid / NXCD; wgid = (xcd < r ? xcd * (q + 1) : r * (q + 1) + (xcd - r) * q) + off; }
;         const int nig = WGM * nN, gid = wgid / nig, fm = gid * WGM, gsz = (nM - fm) < WGM ? (nM - fm) : WGM;
;         u.pm = fm + ((wgid % nig) % gsz); u.pn = (wgid % nig) / gsz; u.mode = 0; return true;
.Lp6_entry:
	s_cmp_lt_u32 s81, 7
	s_cselect_b64 s[0:1], -1, 0
	s_cmpk_gt_i32 s82, 0x127
	v_readfirstlane_b32 s24, v244
	s_cbranch_scc1 .LBB0_96
	v_lshlrev_b32_e32 v0, 4, v244
	s_waitcnt vmcnt(0)
	v_add_u32_e32 v3, 0x2000, v0
	v_ashrrev_i32_e32 v2, 31, v3
	v_lshrrev_b32_e32 v2, 22, v2
	v_add_u32_e32 v2, v3, v2
	v_ashrrev_i32_e32 v2, 10, v2
	v_mul_i32_i24_e32 v4, 0x400, v2
	v_sub_u32_e32 v3, v3, v4
	v_lshrrev_b32_e32 v4, 4, v3
	v_bitop3_b32 v4, v4, v3, 32 bitop3:0x6c
	v_readlane_b32 s6, v254, 46
	v_ashrrev_i32_e32 v3, 31, v4
	v_readlane_b32 s7, v254, 47
	s_mov_b32 s8, s6
	v_lshrrev_b32_e32 v3, 26, v3
	s_mov_b32 s7, s91
	v_writelane_b32 v254, s8, 46
	v_add_u32_e32 v5, v4, v3
	v_lshlrev_b32_e32 v6, 3, v2
	v_writelane_b32 v254, s9, 47
	s_lshl_b64 s[6:7], s[6:7], 23
	v_readlane_b32 s8, v253, 47
	v_ashrrev_i32_e32 v3, 6, v5
	v_and_b32_e32 v6, -16, v6
	s_add_u32 s25, s8, s6
	v_readlane_b32 s6, v253, 48
	v_add_u32_e32 v6, v3, v6
	s_addc_u32 s26, s6, s7
	v_and_b32_e32 v7, 3, v3
	s_mov_b32 s6, 0xfffe0
	v_lshrrev_b32_e32 v8, 2, v6
	v_lshlrev_b32_e32 v9, 1, v6
	v_and_b32_e32 v5, 0xc0, v5
	v_and_or_b32 v7, v6, s6, v7
	v_and_b32_e32 v8, 4, v8
	v_and_b32_e32 v9, 24, v9
	v_sub_u32_e32 v4, v4, v5
	v_or3_b32 v7, v7, v8, v9
	v_lshlrev_b32_e32 v8, 5, v2
	v_ashrrev_i16_sdwa v4, v236, sext(v4) dst_sel:DWORD dst_unused:UNUSED_PAD src0_sel:DWORD src1_sel:BYTE_0
	v_and_b32_e32 v8, 32, v8
	v_bfe_i32 v4, v4, 0, 16
	v_add_lshl_u32 v5, v8, v4, 1
	v_lshl_add_u32 v178, v7, 12, v5
	v_lshl_add_u32 v180, v6, 12, v5
	v_bfe_i32 v5, v244, 27, 1
	v_lshrrev_b32_e32 v5, 22, v5
	v_add_u32_e32 v5, v0, v5
	v_and_b32_e32 v5, 0xfffffc00, v5
	v_sub_u32_e32 v0, v0, v5
	v_lshrrev_b32_e32 v5, 4, v0
	v_ashrrev_i32_e32 v6, 31, v244
	v_bitop3_b32 v0, v5, v0, 32 bitop3:0x6c
	v_lshrrev_b32_e32 v6, 26, v6
	v_ashrrev_i32_e32 v5, 31, v0
	v_add_u32_e32 v6, v244, v6
	v_lshrrev_b32_e32 v5, 26, v5
	v_ashrrev_i32_e32 v6, 6, v6
	v_add_u32_e32 v7, v0, v5
	v_lshlrev_b32_e32 v8, 3, v6
	v_ashrrev_i32_e32 v5, 6, v7
	v_and_b32_e32 v8, -16, v8
	v_add_u32_e32 v8, v5, v8
	v_and_b32_e32 v9, 3, v5
	s_ashr_i32 s28, s82, 31
	v_and_or_b32 v9, v8, s6, v9
	s_lshr_b32 s6, s28, 29
	s_add_i32 s6, s82, s6
	s_ashr_i32 s7, s24, 6
	s_ashr_i32 s8, s6, 3
	s_and_b32 s6, s6, -8
	s_ashr_i32 s10, s24, 8
	s_lshl_b32 s27, s7, 10
	s_sub_i32 s6, s82, s6
	s_cmp_lt_i32 s6, 0
	s_cselect_b32 s9, 38, 37
	s_mul_i32 s6, s9, s6
	s_add_i32 s6, s6, s8
	s_mov_b32 s9, 0
	s_cmpk_lg_u32 s42, 0x100
	s_cbranch_scc1 .Lp6_mapdone
	s_mov_b32 s9, 1
	v_readlane_b32 s8, v255, 5
	s_and_b32 s6, s82, 7
	s_lshl_b32 s6, s6, 5
	s_lshr_b32 s11, s82, 3
	s_add_i32 s6, s6, s11
	s_cmp_eq_u32 s8, 0
	s_cbranch_scc1 .Lp6_noforce
	s_add_i32 s6, s8, 0xd7
	s_mov_b32 s8, 0
	s_nop 0
	v_writelane_b32 v255, s8, 5
	s_branch .Lp6_mapdone

; __device__ __forceinline__ int launder(int v) { asm volatile("" : "+v"(v)); return v; }
; __device__ __forceinline__ void run_phase(const Params& p, int ph, LAS unsigned char* lds, const int tid, const int bid) {
;     ...
;         if (l == 0 && bid >= 40) for (int it = 1440 + bid - 40; it < 2880; it += G - 40) conv_item(p, 1, it, lds, launder(tid)); }
.LBB0_96:
	s_cmpk_lg_u32 s42, 0x100
	s_cbranch_scc1 .Ly3_old96
	s_andn2_b64 vcc, exec, s[0:1]
	s_cbranch_vccnz .LBB0_139
	s_cmp_eq_u32 s81, 6
	s_cbranch_scc0 .LBB0_139
	s_add_i32 s18, s82, 0x5a0
	s_movk_i32 s19, 0x100
	s_movk_i32 s20, 0xb40
	s_mov_b32 s21, 1
	s_mov_b32 s22, 2
	s_branch .Lcva_run

;     __device__ __forceinline__ bool operator()(f32x4 (&acc)[2][2][4][2], const Unit& un, int wr, int wc, int fr, int fq) const {
;     ...
;             asm volatile("s_waitcnt vmcnt(0)" ::: "memory");
;             __builtin_amdgcn_fence(__ATOMIC_RELEASE, "agent");
;             asm volatile("s_waitcnt vmcnt(0)" ::: "memory");
;             if (fr == 0 && fq == 0) __hip_atomic_fetch_add(flag, 1u, __ATOMIC_RELAXED, __HIP_MEMORY_SCOPE_AGENT);
.LBB0_148:
	s_cmp_eq_u32 s81, 11
	s_cbranch_scc1 .Ly3_sig_ok
	s_cmp_eq_u32 s81, 5
	s_cbranch_scc0 .Lp5_nosig
.Ly3_sig_ok:
	s_cmp_eq_u32 s85, 2
	s_cbranch_scc0 .Lp5_nosig
	s_cmpk_lg_u32 s42, 0x100
	s_cbranch_scc1 .Lp5_nosig
	s_and_b32 s22, s82, 7
	s_cmp_lt_u32 s22, 6
	s_cbranch_scc1 .Lp5_nosig
	s_waitcnt vmcnt(0)
	s_barrier
	s_barrier
	s_cmpk_gt_u32 s63, 0x3f
	s_cbranch_scc1 .Lp5_nosig
	v_readlane_b32 s22, v253, 23
	v_readlane_b32 s23, v253, 24
	buffer_wbl2 sc1
	s_waitcnt vmcnt(0)
	s_add_u32 s22, s22, 0x6000
	s_addc_u32 s23, s23, 0
	s_cmp_eq_u32 s81, 5
	s_cbranch_scc0 .Ly3_sig_l1
	s_add_u32 s22, s22, 0x100
	s_addc_u32 s23, s23, 0
.Ly3_sig_l1:
	s_mov_b64 vcc, exec
	s_mov_b64 exec, 1
	s_nop 4
	global_atomic_add v1, v236, s[22:23]
	s_mov_b64 exec, vcc

;     __device__ __forceinline__ bool operator()(f32x4 (&acc)[2][2][4][2], const Unit& un, int wr, int wc, int fr, int fq) const {
;     ...
;             while (__hip_atomic_load(flag, __ATOMIC_RELAXED, __HIP_MEMORY_SCOPE_AGENT) < 8u) { __builtin_amdgcn_s_sleep(2); if (++sp > (1u << 22)) break; }
;             __builtin_amdgcn_fence(__ATOMIC_ACQUIRE, "agent");
;             asm volatile("s_waitcnt vmcnt(0)" ::: "memory");
.Ly3_sh_ok:
	s_cmpk_lg_u32 s42, 0x100
	s_cbranch_scc1 .Lp5_noshadow
	s_cmpk_lt_u32 s82, 0x50
	s_cbranch_scc1 .Lp5_noshadow
	s_cmpk_gt_u32 s82, 0x77
	s_cbranch_scc1 .Lp5_noshadow
	s_cmpk_gt_u32 s63, 0x3f
	s_cbranch_scc1 .Lp5_spun
	v_readlane_b32 s6, v253, 23
	v_readlane_b32 s7, v253, 24
	s_movk_i32 s8, 0x4000
	s_add_u32 s6, s6, 0x6000
	s_addc_u32 s7, s7, 0
	s_cmp_eq_u32 s81, 5
	s_cbranch_scc0 .Ly3_sh_l1
	s_add_u32 s6, s6, 0x100
	s_addc_u32 s7, s7, 0
.Ly3_sh_l1:
	s_nop 4

; __device__ __forceinline__ int launder(int v) { asm volatile("" : "+v"(v)); return v; }
; __device__ __forceinline__ void run_phase(const Params& p, int ph, LAS unsigned char* lds, const int tid, const int bid) {
;     ...
;         if (l == 0 && bid >= 80) for (int it = bid - 80; it < 1440; it += G - 80) conv_item(p, 1, it, lds, launder(tid)); }
.Lp5_noshadow:
	s_cmp_lt_u32 s81, 7
	s_cselect_b64 s[0:1], -1, 0
	s_cmpk_gt_i32 s82, 0x4f
	s_cselect_b64 s[6:7], -1, 0
	s_cmpk_lt_u32 s82, 0x5f0
	s_cselect_b64 s[8:9], -1, 0
	s_and_b64 s[0:1], s[0:1], s[8:9]
	s_and_b64 s[0:1], s[0:1], s[6:7]
	s_andn2_b64 vcc, exec, s[0:1]
	s_cbranch_vccnz .LBB0_281
	s_add_i32 s18, s82, 0xffffffb0
	s_add_i32 s19, s42, 0xffffffb0
	s_movk_i32 s20, 0x5a0
	s_cmpk_lg_u32 s42, 0x100
	s_cbranch_scc1 .Ly3_p5old
	s_add_i32 s18, s82, 0xffffff88
	s_movk_i32 s19, 0x88
	s_movk_i32 s20, 0x5a0
.Ly3_p5old:
	s_mov_b32 s21, 1
	s_mov_b32 s22, 1
	s_branch .Lcva_run
